# barrier census: 16 counter loads issued back to back instead of 16 serial round trips
# baseline (speedup 1.0000x reference)
.LBB0_757:
	v_readlane_b32 s16, v250, 7
	v_readlane_b32 s17, v250, 8
	v_readlane_b32 s10, v253, 37
	s_mov_b64 s[22:23], -1
	s_mov_b64 s[26:27], -1
	s_nop 1
	global_load_dword v0, v1, s[16:17] sc1
	v_readlane_b32 s16, v250, 9
	v_readlane_b32 s17, v250, 10
	s_waitcnt lgkmcnt(0)
	s_nop 3
	global_load_dword v2, v1, s[16:17] sc1
	v_readlane_b32 s16, v250, 11
	v_readlane_b32 s17, v250, 12
	s_nop 1
	s_nop 2
	global_load_dword v3, v1, s[16:17] sc1
	v_readlane_b32 s16, v250, 13
	v_readlane_b32 s17, v250, 14
	s_nop 1
	s_nop 2
	global_load_dword v4, v1, s[16:17] sc1
	v_readlane_b32 s16, v250, 15
	v_readlane_b32 s17, v250, 16
	s_nop 1
	s_nop 2
	global_load_dword v5, v1, s[16:17] sc1
	v_readlane_b32 s16, v250, 17
	v_readlane_b32 s17, v250, 18
	s_nop 1
	s_nop 2
	global_load_dword v6, v1, s[16:17] sc1
	v_readlane_b32 s16, v250, 19
	v_readlane_b32 s17, v250, 20
	s_nop 1
	s_nop 2
	global_load_dword v7, v1, s[16:17] sc1
	v_readlane_b32 s16, v250, 21
	v_readlane_b32 s17, v250, 22
	s_nop 1
	s_nop 2
	global_load_dword v8, v1, s[16:17] sc1
	v_readlane_b32 s16, v250, 23
	v_readlane_b32 s17, v250, 24
	s_nop 1
	s_nop 2
	global_load_dword v9, v1, s[16:17] sc1
	v_readlane_b32 s16, v250, 25
	v_readlane_b32 s17, v250, 26
	s_nop 1
	s_nop 2
	global_load_dword v10, v1, s[16:17] sc1
	v_readlane_b32 s16, v250, 27
	v_readlane_b32 s17, v250, 28
	s_nop 1
	s_nop 2
	global_load_dword v11, v1, s[16:17] sc1
	v_readlane_b32 s16, v250, 29
	v_readlane_b32 s17, v250, 30
	s_nop 1
	s_nop 2
	global_load_dword v12, v1, s[16:17] sc1
	v_readlane_b32 s16, v250, 31
	v_readlane_b32 s17, v250, 32
	s_nop 1
	s_nop 2
	global_load_dword v13, v1, s[16:17] sc1
	v_readlane_b32 s16, v250, 33
	v_readlane_b32 s17, v250, 34
	s_nop 1
	s_nop 2
	global_load_dword v14, v1, s[16:17] sc1
	v_readlane_b32 s16, v250, 35
	v_readlane_b32 s17, v250, 36
	s_nop 1
	s_nop 2
	global_load_dword v15, v1, s[16:17] sc1
	v_readlane_b32 s16, v250, 37
	v_readlane_b32 s17, v250, 38
	s_nop 1
	s_nop 2
	global_load_dword v16, v1, s[16:17] sc1
	s_waitcnt vmcnt(0)
	v_add_u32_e32 v17, v2, v0
	v_add_u32_e32 v17, v17, v3
	v_add_u32_e32 v17, v17, v4
	v_add_u32_e32 v17, v17, v5
	v_add_u32_e32 v17, v17, v6
	v_add_u32_e32 v17, v17, v7
	v_add_u32_e32 v17, v17, v8
	v_add_u32_e32 v17, v17, v9
	v_add_u32_e32 v17, v17, v10
	v_add_u32_e32 v17, v17, v11
	v_add_u32_e32 v17, v17, v12
	v_add_u32_e32 v17, v17, v13
	v_add_u32_e32 v17, v17, v14
	v_add_u32_e32 v17, v17, v15
	v_add_u32_e32 v17, v17, v16
	v_cmp_eq_u32_e32 vcc, s10, v17
	s_cbranch_vccnz .LBB0_756
	s_and_b32 s10, s2, 0xff
	s_cmp_eq_u32 s10, 0
	s_mov_b64 s[30:31], -1
	s_sleep 1
	s_cbranch_scc1 .LBB0_761
	s_and_b64 vcc, exec, s[30:31]
	s_cbranch_vccz .LBB0_756
